# P5 rows aligned to the workgroup's own 256-row tile; the P5-P6 seam also becomes a 4-workgroup group barrier
# speedup vs baseline: 1.0038x; 1.0004x over previous
.LBB0_630:
	s_and_b32 s2, s74, 7
	s_lshl_b32 s2, s2, 3
	s_bfe_u32 s3, s74, 0x30003
	s_add_u32 s2, s2, s3
	s_lshl_b32 s1, s2, 4
	s_lshr_b32 s3, s74, 6
	s_lshl_b32 s3, s3, 2
	s_add_u32 s1, s1, s3
	s_mov_b32 s0, 1
	s_movk_i32 s6, 0x200
	v_lshl_add_u32 v0, s1, 9, v10
	s_add_u32 s2, s1, 4
	s_lshl_b32 s53, s2, 9
	s_sub_u32 s53, s53, 1
	s_ashr_i32 s13, s12, 31
	v_readlane_b32 s16, v254, 10
	s_lshl_b64 s[2:3], s[12:13], 24
	v_readlane_b32 s18, v254, 12
	v_readlane_b32 s17, v254, 11
	v_readlane_b32 s19, v254, 13
	s_add_u32 s16, s18, s2
	v_ashrrev_i32_e32 v1, 31, v0
	s_addc_u32 s17, s19, s3
	v_lshl_add_u64 v[2:3], v[0:1], 4, s[8:9]
	s_mov_b64 s[2:3], 0x9e00000
	s_ashr_i32 s7, s6, 31
	v_lshlrev_b32_e32 v1, 1, v10
	v_lshl_add_u64 v[2:3], v[2:3], 0, s[2:3]
	s_lshl_b64 s[18:19], s[6:7], 4
	v_lshl_add_u32 v4, s1, 10, v1
	s_lshl_b32 s2, s0, 10
	s_mov_b64 s[38:39], 0
	v_mov_b32_e32 v1, v0
	v_readlane_b32 s20, v254, 14
	v_readlane_b32 s21, v254, 15
	v_readlane_b32 s22, v254, 16
	v_readlane_b32 s23, v254, 17
	v_readlane_b32 s24, v254, 18
	v_readlane_b32 s25, v254, 19
	v_readlane_b32 s26, v254, 20
	v_readlane_b32 s27, v254, 21
	v_readlane_b32 s28, v254, 22
	v_readlane_b32 s29, v254, 23
	v_readlane_b32 s30, v254, 24
	v_readlane_b32 s31, v254, 25

.Llb686_go:
	s_and_b32 s0, s74, 63
	s_lshl_b32 s0, s0, 8
	s_add_u32 s0, s0, 0x6000
	s_add_u32 s2, s92, s0
	s_addc_u32 s3, s93, 0
	v_mov_b32_e32 v0, 1
	s_waitcnt vmcnt(0) lgkmcnt(0)
	s_add_u32 s12, s92, 0x5100
	s_addc_u32 s13, s93, 0
	global_atomic_add v197, v0, s[12:13]
	global_atomic_add v1, v197, v0, s[2:3] sc0
	s_waitcnt vmcnt(0)
	v_readfirstlane_b32 s1, v1
	s_lshr_b32 s8, s1, 2
	s_and_b32 s1, s1, 3
	s_cmp_eq_u32 s1, 3
	s_cbranch_scc1 .Llb686_lead
	s_mov_b32 s9, 0
